# residual phases: nt hint added to the 12 sc1 streaming row loads (read-once O / x rows); on v38
# baseline (speedup 1.0000x reference)
; __device__ __forceinline__ void ew_load(EwRow& r, const bf16* __restrict__ xrow16, const bf16* __restrict__ orow, int lane) {
;     const v4u* xr = (const v4u*)xrow16 + lane; const v4u* orr = (const v4u*)orow + lane;
; #pragma unroll
;     for (int j = 0; j < 2; ++j) { r.x[j] = xr[64 * j]; r.o[j] = orr[64 * j]; }
; }
; __global__ void __launch_bounds__(NWAVES * 64, 2) hybrid_fwd(Args args) {
;     ...
;                 { const bool aff = (NGW == 2048); const int x = vcu >> 5, wl = (vcu & 31) * NWAVES + wave;
;                   const int nk = aff ? 8 + (wl < 64 ? 1 : 0) : (gw < MT ? (MT - gw + NGW - 1) / NGW : 0);
;     ...
;                   if (nk > 0) { EwRow r0, r1, r2;
;                     { const int ma = EW_ROW(0); ew_load(r0, X16 + (size_t)ma * 2 * DM, OB + (size_t)ma * OP, lane); }
;                     { const int kb = 1 < nk ? 1 : 0; const int mb = EW_ROW(kb); ew_load(r1, X16 + (size_t)mb * 2 * DM, OB + (size_t)mb * OP, lane); }
; #pragma unroll 1
;                     for (int k = 0; k < nk; ++k) {
;                         { const int kc = k + 2 < nk ? k + 2 : k; const int mc = EW_ROW(kc); ew_load(r2, X16 + (size_t)mc * 2 * DM, OB + (size_t)mc * OP, lane); }
.LBB0_425:
	s_add_i32 s8, s38, -15
	s_cmp_lg_u32 s86, 6
	s_cselect_b64 s[4:5], -1, 0
	s_cmp_lt_u32 s8, -7
	s_cselect_b64 s[8:9], -1, 0
	s_ashr_i32 s10, s10, 5
	s_or_b64 s[4:5], s[8:9], s[4:5]
	s_lshl_b32 s24, s10, 11
	s_xor_b64 s[8:9], s[4:5], -1
	s_add_i32 s18, s12, s24
	s_and_b64 s[14:15], s[6:7], exec
	s_cselect_b32 s14, s18, s2
	s_ashr_i32 s15, s14, 31
	v_readlane_b32 s40, v253, 57
	s_lshl_b64 s[22:23], s[14:15], 12
	v_readlane_b32 s54, v254, 7
	v_readlane_b32 s55, v254, 8
	s_add_u32 s22, s54, s22
	s_addc_u32 s23, s55, s23
	s_lshl_b64 s[14:15], s[14:15], 11
	v_readlane_b32 s26, v253, 32
	v_readlane_b32 s27, v253, 33
	s_add_u32 s14, s26, s14
	s_addc_u32 s15, s27, s15
	v_lshlrev_b32_e32 v128, 4, v134
	s_cmp_eq_u32 s17, 1
	global_load_dwordx4 v[56:59], v128, s[22:23] sc1 nt
	global_load_dwordx4 v[48:51], v128, s[22:23] offset:1024 sc1 nt
	global_load_dwordx4 v[60:63], v128, s[14:15] sc1 nt
	global_load_dwordx4 v[52:55], v128, s[14:15] offset:1024 sc1 nt
	s_cselect_b32 s13, 0, s16
	s_cselect_b32 s14, 0, 0x100
	s_add_i32 s13, s13, s2
	s_add_i32 s14, s18, s14
	s_and_b64 s[6:7], s[6:7], exec
	s_cselect_b32 s6, s14, s13
	s_lshl_b32 s7, s10, 6
	s_add_i32 s21, s12, s7
	s_ashr_i32 s7, s6, 31
	s_lshl_b64 s[12:13], s[6:7], 11
	s_add_u32 s12, s26, s12
	s_addc_u32 s13, s27, s13
	s_lshl_b64 s[6:7], s[6:7], 12
	s_add_u32 s6, s54, s6
	s_addc_u32 s7, s55, s7
	global_load_dwordx4 v[36:39], v128, s[12:13] offset:1024 sc1 nt
	global_load_dwordx4 v[44:47], v128, s[12:13] sc1 nt
	global_load_dwordx4 v[40:43], v128, s[6:7] offset:1024 sc1 nt
	global_load_dwordx4 v[32:35], v128, s[6:7] sc1 nt
	v_lshlrev_b32_e32 v16, 1, v134
	s_add_i32 s10, s70, s24
	s_mov_b32 s19, 0
	v_lshl_add_u64 v[64:65], s[54:55], 0, v[128:129]
	v_lshl_add_u64 v[66:67], s[26:27], 0, v[128:129]
	s_addk_i32 s21, 0x4000
	v_cmp_eq_u32_e64 s[6:7], 0, v134
	s_add_i32 s22, s10, s11
	v_lshlrev_b32_e32 v68, 4, v16
	v_lshlrev_b32_e32 v69, 4, v134
	v_readlane_b32 s41, v253, 58
	v_readlane_b32 s42, v253, 59
	v_readlane_b32 s43, v253, 60
	v_readlane_b32 s44, v253, 61
	v_readlane_b32 s45, v253, 62
	v_readlane_b32 s46, v253, 63
	v_readlane_b32 s47, v254, 0
	v_readlane_b32 s48, v254, 1
	v_readlane_b32 s49, v254, 2
	v_readlane_b32 s50, v254, 3
	v_readlane_b32 s51, v254, 4
	v_readlane_b32 s52, v254, 5
	v_readlane_b32 s53, v254, 6
	s_branch .LBB0_428

; __device__ __forceinline__ void ew_load(EwRow& r, const bf16* __restrict__ xrow16, const bf16* __restrict__ orow, int lane) {
;     const v4u* xr = (const v4u*)xrow16 + lane; const v4u* orr = (const v4u*)orow + lane;
; #pragma unroll
;     for (int j = 0; j < 2; ++j) { r.x[j] = xr[64 * j]; r.o[j] = orr[64 * j]; }
; }
; __global__ void __launch_bounds__(NWAVES * 64, 2) hybrid_fwd(Args args) {
;     ...
;                     for (int k = 0; k < nk; ++k) {
;                         { const int kc = k + 2 < nk ? k + 2 : k; const int mc = EW_ROW(kc); ew_load(r2, X16 + (size_t)mc * 2 * DM, OB + (size_t)mc * OP, lane); }
.LBB0_433:
	s_ashr_i32 s11, s10, 31
	s_lshl_b64 s[12:13], s[10:11], 12
	s_lshl_b64 s[10:11], s[10:11], 11
	v_lshl_add_u64 v[36:37], v[64:65], 0, s[12:13]
	v_lshl_add_u64 v[38:39], v[66:67], 0, s[10:11]
	global_load_dwordx4 v[32:35], v[36:37], off sc1 nt
	global_load_dwordx4 v[40:43], v[36:37], off offset:1024 sc1 nt
	global_load_dwordx4 v[44:47], v[38:39], off sc1 nt
	s_nop 0
	global_load_dwordx4 v[36:39], v[38:39], off offset:1024 sc1 nt
	s_mov_b64 s[12:13], -1
	s_and_b64 vcc, exec, s[0:1]
	s_cbranch_vccz .LBB0_435
	s_mul_i32 s10, s19, s16
	s_add_i32 s10, s10, s2
	s_mov_b64 s[12:13], 0
